# v9 plus RWKV producer P4 reordered (operand reads hoisted, independent MFMAs fill the dependent chain) and ring-slot flag read hoisted
# baseline (speedup 1.0000x reference)
; __device__ __forceinline__ void rw_load4(RwRaw4& x, const bf16* R, const bf16* K, const bf16* V, const bf16* WM, const bf16* A, size_t m, int ch, int vch) {
; #pragma unroll
;     for (int j = 0; j < 4; ++j) { const size_t off = (m + j) * 1024 + ch;
;         x.r[j] = *(const v2u*)(R + off); x.k[j] = *(const v2u*)(K + off); x.wm[j] = *(const v2u*)(WM + off); x.a[j] = *(const v2u*)(A + off); x.v[j] = V[(m + j) * 1024 + vch]; }
; }
; __device__ __forceinline__ void rw_scan(const bf16* R, const bf16* K, const bf16* V, const bf16* WM, const bf16* A, const float* k_k, const float* k_a, bf16* Y, LAS unsigned char* lds) {
;     ...
;             for (int cj = pw; cj < NCH; cj += RW_NPROD) {
;                 {
;                     const RwRaw4 cu = nx;
;                     { const int cn = cj + RW_NPROD < NCH ? cj + RW_NPROD : cj; rw_load4(nx, R, K, V, WM, A, row0 + 16 * (size_t)cn + 4 * fq, ch, vch); }
;                     while ((int)flg[RW_NSLOT] < cj - (RW_NSLOT - 1)) __builtin_amdgcn_s_sleep(2);
.LBB0_496:
	v_mov_b32_e32 v34, s31
	ds_read_b32 v34, v34
	s_add_i32 s73, s89, 7
	s_cmpk_gt_i32 s89, 0x1f8
	s_cselect_b64 s[18:19], -1, 0
	s_cmpk_lt_i32 s89, 0x1f9
	s_cselect_b32 s92, s73, s89
	s_lshl_b64 s[68:69], s[92:93], 14
	v_lshl_add_u64 v[56:57], s[68:69], 0, v[16:17]
	v_or_b32_e32 v20, v56, v12
	v_mov_b32_e32 v21, v57
	v_lshlrev_b64 v[20:21], 1, v[20:21]
	v_lshl_add_u64 v[22:23], s[8:9], 0, v[20:21]
	v_lshl_add_u64 v[36:37], s[10:11], 0, v[20:21]
	v_lshl_add_u64 v[40:41], s[4:5], 0, v[20:21]
	v_lshl_add_u64 v[20:21], s[6:7], 0, v[20:21]
	global_load_dwordx2 v[38:39], v[22:23], off
	s_nop 0
	global_load_dwordx2 v[36:37], v[36:37], off
	s_nop 0
	global_load_dwordx2 v[22:23], v[40:41], off
	s_nop 0
	global_load_dwordx2 v[20:21], v[20:21], off
	v_or_b32_e32 v40, v56, v18
	v_mov_b32_e32 v41, v57
	v_lshlrev_b64 v[40:41], 1, v[40:41]
	v_lshl_add_u64 v[44:45], v[56:57], 1, v[14:15]
	v_lshl_add_u64 v[42:43], s[8:9], 0, v[40:41]
	v_or_b32_e32 v52, 0x800, v56
	v_lshl_add_u64 v[46:47], s[10:11], 0, v[40:41]
	v_lshl_add_u64 v[48:49], s[4:5], 0, v[40:41]
	v_lshl_add_u64 v[50:51], s[6:7], 0, v[40:41]
	global_load_ushort v13, v[44:45], off
	s_nop 0
	global_load_dwordx2 v[42:43], v[42:43], off
	s_nop 0
	global_load_dwordx2 v[40:41], v[46:47], off
	global_load_ushort v19, v[44:45], off offset:2048
	v_or_b32_e32 v44, v52, v12
	v_mov_b32_e32 v45, v57
	v_mov_b32_e32 v53, v57
	v_lshlrev_b64 v[54:55], 1, v[44:45]
	v_or_b32_e32 v56, 0xc00, v56
	v_lshl_add_u64 v[58:59], s[8:9], 0, v[54:55]
	v_lshl_add_u64 v[60:61], s[10:11], 0, v[54:55]
	v_lshl_add_u64 v[62:63], v[52:53], 1, v[14:15]
	v_or_b32_e32 v52, v56, v12
	global_load_dwordx2 v[46:47], v[48:49], off
	global_load_dwordx2 v[44:45], v[50:51], off
	s_nop 0
	global_load_dwordx2 v[50:51], v[58:59], off
	global_load_dwordx2 v[48:49], v[60:61], off
	v_lshl_add_u64 v[58:59], s[4:5], 0, v[54:55]
	v_lshl_add_u64 v[60:61], s[6:7], 0, v[54:55]
	v_lshlrev_b64 v[72:73], 1, v[52:53]
	v_lshl_add_u64 v[82:83], s[8:9], 0, v[72:73]
	global_load_dwordx2 v[54:55], v[58:59], off
	global_load_dwordx2 v[52:53], v[60:61], off
	global_load_ushort v31, v[62:63], off
	s_nop 0
	global_load_dwordx2 v[58:59], v[82:83], off
	v_lshl_add_u64 v[60:61], s[10:11], 0, v[72:73]
	v_lshl_add_u64 v[82:83], s[4:5], 0, v[72:73]
	v_lshl_add_u64 v[72:73], s[6:7], 0, v[72:73]
	v_lshl_add_u64 v[86:87], v[56:57], 1, v[14:15]
	global_load_dwordx2 v[62:63], v[60:61], off
	s_nop 0
	global_load_dwordx2 v[60:61], v[82:83], off
	global_load_dwordx2 v[56:57], v[72:73], off
	global_load_ushort v198, v[86:87], off
	s_add_i32 s68, s89, -8
	s_waitcnt lgkmcnt(0)
	v_cmp_le_i32_e32 vcc, s68, v34
	s_cbranch_vccnz .LBB0_498
